# o51: FF2(L0)->in-proj(L1) seam split: early full-counter arrive after last H read (WAR) + group seam K3 for RAW
# baseline (speedup 1.0000x reference)
; __device__ __forceinline__ int lane_id() { int l; asm volatile("v_mbcnt_lo_u32_b32 %0, -1, 0\n\tv_mbcnt_hi_u32_b32 %0, -1, %0" : "=v"(l)); return l; }
; __device__ __forceinline__ void xb_add_l2(unsigned* p, unsigned v) { (void)__hip_atomic_fetch_add(p, v, __ATOMIC_RELAXED, __HIP_MEMORY_SCOPE_WORKGROUP); }
; __device__ __forceinline__ unsigned xb_xcc_id() { return (unsigned)__builtin_amdgcn_s_getreg((3 << 11) | 20) & 0xFu; }
; __device__ __forceinline__ void xcd_local_barrier(unsigned* bar, volatile LAS unsigned* st, int wid0) {
;     ...
;     if (wid0 == 0 && lane_id() == 0) {
;         unsigned zo = 0; asm volatile("" : "+s"(zo));
;         unsigned* cnt = bar + zo + XB_LCNT2(xb_xcc_id());
;         const unsigned e = st[6] + 1u; st[6] = e; const unsigned target = e * st[4];
;         xb_add_l2(cnt, 1u);
.LBB13_1190:
	s_and_b64 vcc, exec, s[22:23]
	s_cbranch_vccnz .Lea5_skip
	s_cmp_gt_i32 s89, 9
	s_cbranch_scc0 .Lea5_skip
	v_readlane_b32 s64, v238, 10
	v_readlane_b32 s65, v238, 11
	s_and_b64 vcc, exec, s[64:65]
	s_cbranch_vccnz .Lea5_skip
	s_add_i32 s66, 0, 0x2117c
	v_mov_b32_e32 v216, s66
	ds_read_b32 v216, v216
	s_add_i32 s66, 0, 0x21178
	v_mov_b32_e32 v217, s66
	ds_read_b32 v218, v217
	s_waitcnt lgkmcnt(0)
	v_readfirstlane_b32 s66, v216
	s_cmp_eq_u32 s66, 0
	s_cbranch_scc1 .Lea5_skip
	s_load_dword s66, s[86:87], 0xb8
	s_load_dwordx2 s[68:69], s[86:87], 0xa8
	v_mbcnt_lo_u32_b32 v216, -1, 0
	v_mbcnt_hi_u32_b32 v216, -1, v216
	v_cmp_eq_u32_e32 vcc, 0, v216
	s_and_saveexec_b64 s[70:71], vcc
	v_add_u32_e32 v218, 1, v218
	ds_write_b32 v217, v218
	s_waitcnt lgkmcnt(0)
	s_mulk_i32 s66, 0xd80
	s_ashr_i32 s67, s66, 31
	s_lshl_b64 s[66:67], s[66:67], 2
	s_add_u32 s68, s68, s66
	s_addc_u32 s69, s69, s67
	s_add_u32 s68, s68, 0x4000
	s_addc_u32 s69, s69, 0
	s_getreg_b32 s66, hwreg(HW_REG_XCC_ID, 0, 4)
	s_lshl_b32 s66, s66, 8
	s_and_b32 s66, s66, 0xf00
	s_add_u32 s68, s68, s66
	s_addc_u32 s69, s69, 0
	s_add_u32 s68, s68, 0xb200
	s_addc_u32 s69, s69, 0
	v_mov_b32_e32 v216, 0
	v_mov_b32_e32 v219, 1
	global_atomic_add v216, v219, s[68:69]
	s_mov_b64 exec, s[70:71]

; __device__ __forceinline__ int lane_id() { int l; asm volatile("v_mbcnt_lo_u32_b32 %0, -1, 0\n\tv_mbcnt_hi_u32_b32 %0, -1, %0" : "=v"(l)); return l; }
; #define LAS __attribute__((address_space(3)))
; __device__ __forceinline__ void xb_add_l2(unsigned* p, unsigned v) { (void)__hip_atomic_fetch_add(p, v, __ATOMIC_RELAXED, __HIP_MEMORY_SCOPE_WORKGROUP); }
; __device__ __forceinline__ unsigned xb_ld_l2(unsigned* p) { unsigned v; const unsigned z = 0u; asm volatile("global_atomic_add %0, %1, %2, off sc0\n\ts_waitcnt vmcnt(0)" : "=v"(v) : "v"(p), "v"(z) : "memory"); return v; }
; __device__ __forceinline__ unsigned xb_xcc_id() { return (unsigned)__builtin_amdgcn_s_getreg((3 << 11) | 20) & 0xFu; }
; #define XB_SPIN(cond, bar) do { unsigned _sp = 0; while (cond) { __builtin_amdgcn_s_sleep(1); \
;     if ((++_sp & 255u) == 0u) { if (xb_ld(&(bar)[XB_TMO])) break; if (_sp > XB_SPIN_CAP) { atomicAdd(&(bar)[XB_TMO], 1u); break; } } } } while (0)
; __device__ __forceinline__ void xcd_local_barrier(unsigned* bar, volatile LAS unsigned* st, int wid0) {
;     asm volatile("s_waitcnt vmcnt(0)" ::: "memory");
;     __syncthreads();
;     if (wid0 == 0 && lane_id() == 0) {
;         unsigned zo = 0; asm volatile("" : "+s"(zo));
;         unsigned* cnt = bar + zo + XB_LCNT2(xb_xcc_id());
;         const unsigned e = st[6] + 1u; st[6] = e; const unsigned target = e * st[4];
;         xb_add_l2(cnt, 1u);
;         XB_SPIN(xb_ld_l2(cnt) < target, bar);
;         __builtin_amdgcn_fence(__ATOMIC_ACQUIRE, "agent");
;         asm volatile("s_waitcnt vmcnt(0)" ::: "memory");
;     }
;     __syncthreads();
.LBB13_1210:
	s_cmp_gt_i32 s89, 9
	s_cselect_b64 s[2:3], -1, 0
	s_and_b64 s[0:1], s[0:1], s[2:3]
	s_andn2_b64 vcc, exec, s[0:1]
	s_cbranch_vccnz .LBB13_1290
	s_load_dword s4, s[86:87], 0xb8
	s_load_dwordx2 s[0:1], s[86:87], 0xa8
	s_getreg_b32 s22, hwreg(HW_REG_XCC_ID, 0, 4)
	s_waitcnt lgkmcnt(0)
	s_mulk_i32 s4, 0xd80
	s_ashr_i32 s5, s4, 31
	s_lshl_b64 s[4:5], s[4:5], 2
	s_add_u32 s0, s0, s4
	s_addc_u32 s1, s1, s5
	s_add_u32 s4, s0, 0x4000
	s_addc_u32 s5, s1, 0
	s_add_i32 s0, 0, 0x2117c
	s_waitcnt vmcnt(0)
	v_mov_b32_e32 v0, s0
	ds_read_b32 v0, v0
	s_waitcnt lgkmcnt(0)
	v_readfirstlane_b32 s0, v0
	s_cmp_eq_u32 s0, 0
	s_cbranch_scc1 .LBB13_1226
	s_waitcnt vmcnt(0)
	v_readlane_b32 s0, v238, 10
	v_readlane_b32 s1, v238, 11
	s_and_b64 vcc, exec, s[0:1]
	s_barrier
	s_cbranch_vccnz .LBB13_1233
	v_mbcnt_lo_u32_b32 v0, -1, 0
	v_mbcnt_hi_u32_b32 v0, -1, v0
	s_mov_b32 s9, 0
	v_cmp_eq_u32_e32 vcc, 0, v0
	s_and_saveexec_b64 s[0:1], vcc
	s_cbranch_execz .LBB13_1232
	s_mov_b32 s8, 0
	s_lshl_b64 s[8:9], s[8:9], 2
	s_add_u32 s8, s4, s8
	s_getreg_b32 s10, hwreg(HW_REG_XCC_ID, 0, 4)
	s_addc_u32 s9, s5, s9
	s_lshl_b32 s10, s10, 8
	s_and_b32 s10, s10, 0xf00
	s_add_u32 s8, s8, s10
	s_addc_u32 s9, s9, 0
	s_add_u32 s8, s8, 0xc200
	s_addc_u32 s9, s9, 0
	s_add_i32 s10, 0, 0x2116c
	v_mov_b32_e32 v1, s10
	ds_read_b32 v0, v1
	s_add_i32 s10, 0, 0x21170
	s_mov_b64 s[6:7], exec
	v_mbcnt_lo_u32_b32 v2, s6, 0
	v_mbcnt_hi_u32_b32 v2, s7, v2
	s_waitcnt lgkmcnt(0)
	v_and_b32_e32 v0, 7, v0
	v_lshlrev_b32_e32 v6, 12, v0
	v_mov_b32_e32 v1, s10
	ds_read_b32 v1, v1
	s_mov_b32 s23, 1
	v_cmp_eq_u32_e32 vcc, 0, v2
	s_and_saveexec_b64 s[10:11], vcc
	s_cbranch_execz .LBB13_1216
	s_bcnt1_i32_b64 s6, s[6:7]
	v_mov_b32_e32 v2, 0
	v_mov_b32_e32 v3, s6
	global_atomic_add v6, v3, s[8:9]

; __device__ __forceinline__ void xb_add_l2(unsigned* p, unsigned v) { (void)__hip_atomic_fetch_add(p, v, __ATOMIC_RELAXED, __HIP_MEMORY_SCOPE_WORKGROUP); }
; __device__ __forceinline__ unsigned xb_ld_l2(unsigned* p) { unsigned v; const unsigned z = 0u; asm volatile("global_atomic_add %0, %1, %2, off sc0\n\ts_waitcnt vmcnt(0)" : "=v"(v) : "v"(p), "v"(z) : "memory"); return v; }
; #define XB_SPIN(cond, bar) do { unsigned _sp = 0; while (cond) { __builtin_amdgcn_s_sleep(1); \
;     if ((++_sp & 255u) == 0u) { if (xb_ld(&(bar)[XB_TMO])) break; if (_sp > XB_SPIN_CAP) { atomicAdd(&(bar)[XB_TMO], 1u); break; } } } } while (0)
; __device__ __forceinline__ void xcd_local_barrier(unsigned* bar, volatile LAS unsigned* st, int wid0) {
;     ...
;         const unsigned e = st[6] + 1u; st[6] = e; const unsigned target = e * st[4];
;         xb_add_l2(cnt, 1u);
;         XB_SPIN(xb_ld_l2(cnt) < target, bar);
;         __builtin_amdgcn_fence(__ATOMIC_ACQUIRE, "agent");
;         asm volatile("s_waitcnt vmcnt(0)" ::: "memory");
.LBB13_1231:
	s_or_b64 exec, exec, s[6:7]
	s_getreg_b32 s10, hwreg(HW_REG_XCC_ID, 0, 4)
	s_lshl_b32 s10, s10, 8
	s_and_b32 s10, s10, 0xf00
	s_add_u32 s8, s4, s10
	s_addc_u32 s9, s5, 0
	s_add_u32 s8, s8, 0xb200
	s_addc_u32 s9, s9, 0
	s_add_i32 s10, 0, 0x21178
	v_mov_b32_e32 v1, s10
	ds_read_b32 v0, v1
	s_add_i32 s10, 0, 0x21170
	v_mov_b32_e32 v1, s10
	ds_read_b32 v1, v1
	v_mov_b32_e32 v3, 0
	s_waitcnt lgkmcnt(0)
	v_mul_lo_u32 v2, v1, v0
	v_mov_b64_e32 v[0:1], s[8:9]
	s_mov_b32 s10, 0
.Lgs5_loop:
	global_atomic_add v4, v[0:1], v3, off sc0
	s_waitcnt vmcnt(0)
	v_cmp_lt_u32_e32 vcc, v4, v2
	s_cbranch_vccz .Lgs5_done
	s_sleep 1
	s_add_i32 s10, s10, 1
	s_cmp_lt_u32 s10, 0x100000
	s_cbranch_scc1 .Lgs5_loop
.Lgs5_done:
	s_waitcnt vmcnt(0)
	buffer_inv sc1
	s_waitcnt vmcnt(0)

; __device__ __forceinline__ int lane_id() { int l; asm volatile("v_mbcnt_lo_u32_b32 %0, -1, 0\n\tv_mbcnt_hi_u32_b32 %0, -1, %0" : "=v"(l)); return l; }
; #define LAS __attribute__((address_space(3)))
; __device__ __forceinline__ void xb_add_l2(unsigned* p, unsigned v) { (void)__hip_atomic_fetch_add(p, v, __ATOMIC_RELAXED, __HIP_MEMORY_SCOPE_WORKGROUP); }
; __device__ __forceinline__ unsigned xb_ld_l2(unsigned* p) { unsigned v; const unsigned z = 0u; asm volatile("global_atomic_add %0, %1, %2, off sc0\n\ts_waitcnt vmcnt(0)" : "=v"(v) : "v"(p), "v"(z) : "memory"); return v; }
; __device__ __forceinline__ unsigned xb_xcc_id() { return (unsigned)__builtin_amdgcn_s_getreg((3 << 11) | 20) & 0xFu; }
; #define XB_SPIN(cond, bar) do { unsigned _sp = 0; while (cond) { __builtin_amdgcn_s_sleep(1); \
;     if ((++_sp & 255u) == 0u) { if (xb_ld(&(bar)[XB_TMO])) break; if (_sp > XB_SPIN_CAP) { atomicAdd(&(bar)[XB_TMO], 1u); break; } } } } while (0)
; __device__ __forceinline__ void xcd_local_barrier(unsigned* bar, volatile LAS unsigned* st, int wid0) {
;     asm volatile("s_waitcnt vmcnt(0)" ::: "memory");
;     __syncthreads();
;     if (wid0 == 0 && lane_id() == 0) {
;         unsigned zo = 0; asm volatile("" : "+s"(zo));
;         unsigned* cnt = bar + zo + XB_LCNT2(xb_xcc_id());
;         const unsigned e = st[6] + 1u; st[6] = e; const unsigned target = e * st[4];
;         xb_add_l2(cnt, 1u);
;         XB_SPIN(xb_ld_l2(cnt) < target, bar);
;         __builtin_amdgcn_fence(__ATOMIC_ACQUIRE, "agent");
;         asm volatile("s_waitcnt vmcnt(0)" ::: "memory");
;     }
;     __syncthreads();
.LBB13_1946:
	s_cmp_gt_i32 s89, 14
	s_cselect_b64 s[2:3], -1, 0
	s_and_b64 s[0:1], s[0:1], s[2:3]
	s_andn2_b64 vcc, exec, s[0:1]
	s_cbranch_vccnz .LBB13_2026
	s_load_dword s4, s[86:87], 0xb8
	s_load_dwordx2 s[0:1], s[86:87], 0xa8
	s_getreg_b32 s22, hwreg(HW_REG_XCC_ID, 0, 4)
	s_waitcnt lgkmcnt(0)
	s_mulk_i32 s4, 0xd80
	s_ashr_i32 s5, s4, 31
	s_lshl_b64 s[4:5], s[4:5], 2
	s_add_u32 s0, s0, s4
	s_addc_u32 s1, s1, s5
	s_add_u32 s4, s0, 0x4000
	s_addc_u32 s5, s1, 0
	s_add_i32 s0, 0, 0x2117c
	v_mov_b32_e32 v0, s0
	ds_read_b32 v0, v0
	s_waitcnt lgkmcnt(0)
	v_readfirstlane_b32 s0, v0
	s_cmp_eq_u32 s0, 0
	s_cbranch_scc1 .LBB13_1962
	s_waitcnt vmcnt(0)
	v_readlane_b32 s0, v238, 10
	v_readlane_b32 s1, v238, 11
	s_and_b64 vcc, exec, s[0:1]
	s_barrier
	s_cbranch_vccnz .LBB13_1969
	v_mbcnt_lo_u32_b32 v0, -1, 0
	v_mbcnt_hi_u32_b32 v0, -1, v0
	s_mov_b32 s9, 0
	v_cmp_eq_u32_e32 vcc, 0, v0
	s_and_saveexec_b64 s[0:1], vcc
	s_cbranch_execz .LBB13_1968
	s_mov_b32 s8, 0
	s_lshl_b64 s[8:9], s[8:9], 2
	s_add_u32 s8, s4, s8
	s_getreg_b32 s10, hwreg(HW_REG_XCC_ID, 0, 4)
	s_addc_u32 s9, s5, s9
	s_lshl_b32 s10, s10, 8
	s_and_b32 s10, s10, 0xf00
	s_add_u32 s8, s8, s10
	s_addc_u32 s9, s9, 0
	s_add_u32 s8, s8, 0xc200
	s_addc_u32 s9, s9, 0
	s_add_i32 s10, 0, 0x2116c
	v_mov_b32_e32 v1, s10
	ds_read_b32 v0, v1
	s_add_i32 s10, 0, 0x21170
	s_mov_b64 s[6:7], exec
	s_waitcnt vmcnt(0)
	v_mbcnt_lo_u32_b32 v2, s6, 0
	v_mbcnt_hi_u32_b32 v2, s7, v2
	s_waitcnt lgkmcnt(0)
	v_and_b32_e32 v0, 7, v0
	v_lshlrev_b32_e32 v6, 12, v0
	v_mov_b32_e32 v1, s10
	ds_read_b32 v1, v1
	s_mov_b32 s23, 1
	v_cmp_eq_u32_e32 vcc, 0, v2
	s_and_saveexec_b64 s[10:11], vcc
	s_cbranch_execz .LBB13_1952
	s_bcnt1_i32_b64 s6, s[6:7]
	v_mov_b32_e32 v2, 0
	v_mov_b32_e32 v3, s6
	global_atomic_add v6, v3, s[8:9]
.LBB13_1952:
	s_or_b64 exec, exec, s[10:11]
	s_waitcnt lgkmcnt(0)
	v_lshrrev_b32_e32 v1, 3, v1
	v_mul_u32_u24_e32 v2, 4, v1
	s_mov_b64 s[6:7], 0
	v_mov_b32_e32 v3, 0
	v_mov_b32_e32 v7, 0
	v_mov_b64_e32 v[0:1], s[8:9]
	s_nop 0
	v_lshl_add_u64 v[0:1], v[0:1], 0, v[6:7]
	s_branch .LBB13_1955

; __device__ __forceinline__ int lane_id() { int l; asm volatile("v_mbcnt_lo_u32_b32 %0, -1, 0\n\tv_mbcnt_hi_u32_b32 %0, -1, %0" : "=v"(l)); return l; }
; #define LAS __attribute__((address_space(3)))
; __device__ __forceinline__ void xb_add_l2(unsigned* p, unsigned v) { (void)__hip_atomic_fetch_add(p, v, __ATOMIC_RELAXED, __HIP_MEMORY_SCOPE_WORKGROUP); }
; __device__ __forceinline__ unsigned xb_ld_l2(unsigned* p) { unsigned v; const unsigned z = 0u; asm volatile("global_atomic_add %0, %1, %2, off sc0\n\ts_waitcnt vmcnt(0)" : "=v"(v) : "v"(p), "v"(z) : "memory"); return v; }
; __device__ __forceinline__ unsigned xb_xcc_id() { return (unsigned)__builtin_amdgcn_s_getreg((3 << 11) | 20) & 0xFu; }
; #define XB_SPIN(cond, bar) do { unsigned _sp = 0; while (cond) { __builtin_amdgcn_s_sleep(1); \
;     if ((++_sp & 255u) == 0u) { if (xb_ld(&(bar)[XB_TMO])) break; if (_sp > XB_SPIN_CAP) { atomicAdd(&(bar)[XB_TMO], 1u); break; } } } } while (0)
; __device__ __forceinline__ void xcd_local_barrier(unsigned* bar, volatile LAS unsigned* st, int wid0) {
;     asm volatile("s_waitcnt vmcnt(0)" ::: "memory");
;     __syncthreads();
;     if (wid0 == 0 && lane_id() == 0) {
;         unsigned zo = 0; asm volatile("" : "+s"(zo));
;         unsigned* cnt = bar + zo + XB_LCNT2(xb_xcc_id());
;         const unsigned e = st[6] + 1u; st[6] = e; const unsigned target = e * st[4];
;         xb_add_l2(cnt, 1u);
;         XB_SPIN(xb_ld_l2(cnt) < target, bar);
;         __builtin_amdgcn_fence(__ATOMIC_ACQUIRE, "agent");
;         asm volatile("s_waitcnt vmcnt(0)" ::: "memory");
;     }
;     __syncthreads();
.LBB13_2063:
	s_cmp_gt_i32 s89, 15
	s_cselect_b64 s[2:3], -1, 0
	s_and_b64 s[0:1], s[0:1], s[2:3]
	s_andn2_b64 vcc, exec, s[0:1]
	s_cbranch_vccnz .LBB13_2143
	s_load_dword s4, s[86:87], 0xb8
	s_load_dwordx2 s[0:1], s[86:87], 0xa8
	s_getreg_b32 s22, hwreg(HW_REG_XCC_ID, 0, 4)
	s_waitcnt lgkmcnt(0)
	s_mulk_i32 s4, 0xd80
	s_ashr_i32 s5, s4, 31
	s_lshl_b64 s[4:5], s[4:5], 2
	s_add_u32 s0, s0, s4
	s_addc_u32 s1, s1, s5
	s_add_u32 s4, s0, 0x4000
	s_addc_u32 s5, s1, 0
	s_add_i32 s0, 0, 0x2117c
	s_waitcnt vmcnt(0)
	v_mov_b32_e32 v0, s0
	ds_read_b32 v0, v0
	s_waitcnt lgkmcnt(0)
	v_readfirstlane_b32 s0, v0
	s_cmp_eq_u32 s0, 0
	s_cbranch_scc1 .LBB13_2079
	s_waitcnt vmcnt(0)
	v_readlane_b32 s0, v238, 10
	v_readlane_b32 s1, v238, 11
	s_and_b64 vcc, exec, s[0:1]
	s_barrier
	s_cbranch_vccnz .LBB13_2086
	v_mbcnt_lo_u32_b32 v0, -1, 0
	v_mbcnt_hi_u32_b32 v0, -1, v0
	s_mov_b32 s9, 0
	v_cmp_eq_u32_e32 vcc, 0, v0
	s_and_saveexec_b64 s[0:1], vcc
	s_cbranch_execz .LBB13_2085
	s_mov_b32 s8, 0
	s_lshl_b64 s[8:9], s[8:9], 2
	s_add_u32 s8, s4, s8
	s_getreg_b32 s10, hwreg(HW_REG_XCC_ID, 0, 4)
	s_addc_u32 s9, s5, s9
	s_lshl_b32 s10, s10, 8
	s_and_b32 s10, s10, 0xf00
	s_add_u32 s8, s8, s10
	s_addc_u32 s9, s9, 0
	s_add_u32 s8, s8, 0xc200
	s_addc_u32 s9, s9, 0
	s_add_i32 s10, 0, 0x2116c
	v_mov_b32_e32 v1, s10
	ds_read_b32 v0, v1
	s_add_i32 s10, 0, 0x21170
	s_mov_b64 s[6:7], exec
	v_mbcnt_lo_u32_b32 v2, s6, 0
	v_mbcnt_hi_u32_b32 v2, s7, v2
	s_waitcnt lgkmcnt(0)
	v_and_b32_e32 v0, 7, v0
	v_lshlrev_b32_e32 v6, 12, v0
	v_mov_b32_e32 v1, s10
	ds_read_b32 v1, v1
	s_mov_b32 s23, 1
	v_cmp_eq_u32_e32 vcc, 0, v2
	s_and_saveexec_b64 s[10:11], vcc
	s_cbranch_execz .LBB13_2069
	s_bcnt1_i32_b64 s6, s[6:7]
	v_mov_b32_e32 v2, 0
	v_mov_b32_e32 v3, s6
	global_atomic_add v6, v3, s[8:9]
.LBB13_2069:
	s_or_b64 exec, exec, s[10:11]
	s_waitcnt lgkmcnt(0)
	v_lshrrev_b32_e32 v1, 3, v1
	v_mul_u32_u24_e32 v2, 5, v1
	s_mov_b64 s[6:7], 0
	v_mov_b32_e32 v3, 0
	v_mov_b32_e32 v7, 0
	v_mov_b64_e32 v[0:1], s[8:9]
	s_nop 0
	v_lshl_add_u64 v[0:1], v[0:1], 0, v[6:7]
	s_branch .LBB13_2072

; __device__ __forceinline__ int lane_id() { int l; asm volatile("v_mbcnt_lo_u32_b32 %0, -1, 0\n\tv_mbcnt_hi_u32_b32 %0, -1, %0" : "=v"(l)); return l; }
; #define LAS __attribute__((address_space(3)))
; __device__ __forceinline__ void xb_add_l2(unsigned* p, unsigned v) { (void)__hip_atomic_fetch_add(p, v, __ATOMIC_RELAXED, __HIP_MEMORY_SCOPE_WORKGROUP); }
; __device__ __forceinline__ unsigned xb_ld_l2(unsigned* p) { unsigned v; const unsigned z = 0u; asm volatile("global_atomic_add %0, %1, %2, off sc0\n\ts_waitcnt vmcnt(0)" : "=v"(v) : "v"(p), "v"(z) : "memory"); return v; }
; __device__ __forceinline__ unsigned xb_xcc_id() { return (unsigned)__builtin_amdgcn_s_getreg((3 << 11) | 20) & 0xFu; }
; #define XB_SPIN(cond, bar) do { unsigned _sp = 0; while (cond) { __builtin_amdgcn_s_sleep(1); \
;     if ((++_sp & 255u) == 0u) { if (xb_ld(&(bar)[XB_TMO])) break; if (_sp > XB_SPIN_CAP) { atomicAdd(&(bar)[XB_TMO], 1u); break; } } } } while (0)
; __device__ __forceinline__ void xcd_local_barrier(unsigned* bar, volatile LAS unsigned* st, int wid0) {
;     asm volatile("s_waitcnt vmcnt(0)" ::: "memory");
;     __syncthreads();
;     if (wid0 == 0 && lane_id() == 0) {
;         unsigned zo = 0; asm volatile("" : "+s"(zo));
;         unsigned* cnt = bar + zo + XB_LCNT2(xb_xcc_id());
;         const unsigned e = st[6] + 1u; st[6] = e; const unsigned target = e * st[4];
;         xb_add_l2(cnt, 1u);
;         XB_SPIN(xb_ld_l2(cnt) < target, bar);
;         __builtin_amdgcn_fence(__ATOMIC_ACQUIRE, "agent");
;         asm volatile("s_waitcnt vmcnt(0)" ::: "memory");
;     }
;     __syncthreads();
.LBB13_2176:
	s_or_b64 exec, exec, s[10:11]
	s_waitcnt lgkmcnt(0)
	v_lshrrev_b32_e32 v1, 3, v1
	v_mul_u32_u24_e32 v2, 6, v1
	s_mov_b64 s[6:7], 0
	v_mov_b32_e32 v3, 0
	v_mov_b32_e32 v7, 0
	v_mov_b64_e32 v[0:1], s[8:9]
	s_nop 0
	v_lshl_add_u64 v[0:1], v[0:1], 0, v[6:7]
	s_branch .LBB13_2179
